# mLSTM chunk prefetch: saddr-form loads with a stepping scalar base (no per-chunk 64-bit vector address build)
# speedup vs baseline: 1.0129x; 1.0105x over previous
.LBB0_803:
	s_or_b64 exec, exec, s[18:19]
	s_mul_hi_i32 s18, s21, 0x2080000
	s_mul_i32 s21, s21, 0x2080000
	s_add_u32 s19, s12, s21
	s_addc_u32 s18, s13, s18
	s_lshl_b32 s21, s22, 1
	v_and_b32_e32 v84, 15, v110
	s_add_u32 s14, s14, s21
	v_lshlrev_b32_e32 v85, 1, v110
	s_addc_u32 s15, s15, 0
	s_lshl_b32 s20, s20, 4
	v_lshl_or_b32 v93, v111, 4, v84
	v_lshrrev_b32_e32 v86, 4, v82
	v_and_b32_e32 v88, 0xffffff80, v85
	s_add_u32 s62, s14, s20
	v_lshlrev_b32_e32 v85, 2, v82
	v_and_b32_e32 v82, 48, v82
	v_mul_lo_u32 v94, v93, s51
	s_addc_u32 s63, s15, 0
	v_readlane_b32 s24, v255, 4
	s_add_i32 s23, 0, 0x10a00
	v_add3_u32 v137, 0, v94, v82
	v_lshlrev_b32_e32 v94, 2, v93
	v_lshlrev_b32_e32 v141, 9, v86
	v_lshlrev_b32_e32 v89, 1, v84
	v_add_u32_e32 v132, s24, v85
	v_add_u32_e32 v133, s88, v85
	v_add_u32_e32 v134, s23, v85
	v_mul_u32_u24_e32 v92, 0x210, v84
	v_mad_u32_u24 v85, v84, s51, 0
	v_lshlrev_b32_e32 v135, 3, v86
	v_add_u32_e32 v139, s23, v94
	v_add_u32_e32 v95, 0, v141
	s_movk_i32 s23, 0xfe10
	v_mul_i32_i24_e32 v84, 0xfffffe40, v84
	v_add_u32_e32 v136, v85, v82
	v_add_u32_e32 v142, v95, v94
	v_mad_i32_i24 v95, v86, s23, v95
	v_add3_u32 v143, v85, v84, v135
	s_add_i32 s23, 0, 0x10200
	v_and_b32_e32 v85, 7, v110
	s_add_i32 s22, 0, 0x10b80
	v_add_u32_e32 v144, s23, v94
	v_ashrrev_i32_e32 v84, 3, v110
	v_lshlrev_b32_e32 v94, 5, v85
	v_add_lshl_u32 v94, v94, v84, 2
	s_add_u32 s19, s19, s21
	v_add_u32_e32 v145, s23, v94
	v_add_u32_e32 v146, 0, v94
	v_lshlrev_b32_e32 v94, 2, v84
	s_addc_u32 s21, s18, 0
	v_lshlrev_b32_e32 v87, 2, v86
	v_add_u32_e32 v96, s23, v94
	v_add_u32_e32 v148, 0, v94
	v_add_u32_e32 v149, s24, v94
	v_sub_u32_e32 v94, 31, v84
	s_add_u32 s18, s19, s20
	v_cndmask_b32_e64 v150, v94, v84, s[4:5]
	s_addc_u32 s19, s21, 0
	v_lshlrev_b32_e32 v84, 1, v85
	v_mov_b32_e32 v85, v17
	v_add_u32_e32 v154, s88, v82
	v_or_b32_e32 v82, 16, v87
	v_lshl_add_u64 v[84:85], s[18:19], 0, v[84:85]
	s_mov_b64 s[18:19], 0x6aa8000
	v_cmp_le_i32_e64 s[36:37], v82, v93
	v_lshl_add_u32 v158, v82, 2, s88
	v_or_b32_e32 v82, 17, v87
	v_lshl_add_u64 v[106:107], v[84:85], 0, s[18:19]
	s_movk_i32 s18, 0x1070
	v_cmp_le_i32_e64 s[38:39], v82, v93
	v_lshl_add_u32 v159, v82, 2, s88
	v_or_b32_e32 v82, 18, v87
	s_waitcnt lgkmcnt(0)
	v_mad_u32_u24 v84, v86, s18, v95
	v_lshl_add_u32 v153, v83, 4, s22
	v_or_b32_e32 v83, 1, v87
	v_cmp_le_i32_e64 s[40:41], v82, v93
	v_lshl_add_u32 v160, v82, 2, s88
	v_or_b32_e32 v82, 19, v87
	v_add3_u32 v90, 0, v88, v89
	v_and_b32_e32 v91, 31, v110
	v_lshl_add_u32 v151, v86, 5, s88
	v_add3_u32 v152, v84, v88, v89
	v_bfe_u32 v178, v119, 4, 2
	v_bfe_u32 v179, v119, 2, 2
	v_lshl_add_u32 v178, v178, 3, v179
	v_mul_u32_u24_e32 v178, 0x210, v178
	v_and_b32_e32 v179, 3, v119
	v_lshl_add_u32 v178, v179, 3, v178
	v_lshrrev_b32_e32 v179, 6, v119
	v_lshl_add_u32 v178, v179, 7, v178
	v_and_b32_e32 v179, 15, v119
	v_mul_u32_u24_e32 v179, 0x210, v179
	v_lshrrev_b32_e32 v196, 6, v119
	v_lshl_add_u32 v179, v196, 7, v179
	v_bfe_u32 v196, v119, 4, 2
	v_lshl_add_u32 v179, v196, 3, v179
	v_lshl_add_u64 v[108:109], s[16:17], 0, v[16:17]
	s_mov_b64 s[98:99], s[16:17]
	v_mul_u32_u24_e32 v16, 0x840, v86
	v_mul_u32_u24_e32 v84, 0x210, v83
	v_or_b32_e32 v85, 2, v87
	v_or_b32_e32 v86, 3, v87
	v_cmp_le_i32_e64 s[42:43], v82, v93
	v_lshl_add_u32 v161, v82, 2, s88
	v_mov_b32_e32 v82, 0
	v_cmp_gt_u32_e64 s[12:13], 64, v110
	v_lshl_add_u32 v131, v91, 4, s22
	v_cmp_lt_i32_e64 s[14:15], 1, v111
	v_add_u32_e32 v138, 0xffffbe00, v137
	v_add_u32_e32 v140, 0xffffff80, v139
	v_add_u32_e32 v147, 0x400, v96
	s_mov_b32 s52, 0
	v_cmp_eq_u32_e64 s[16:17], 0, v91
	v_cmp_gt_u32_e64 s[18:19], 2, v91
	v_cmp_gt_u32_e64 s[20:21], 4, v91
	v_cmp_gt_u32_e64 s[22:23], 8, v91
	v_cmp_gt_u32_e64 s[24:25], 16, v91
	v_cmp_le_i32_e64 s[26:27], v87, v93
	v_cmp_lt_i32_e64 s[28:29], v87, v93
	v_lshl_add_u32 v155, v83, 2, s88
	v_cmp_le_i32_e64 s[30:31], v85, v93
	v_lshl_add_u32 v156, v85, 2, s88
	v_cmp_le_i32_e64 s[34:35], v86, v93
	v_lshl_add_u32 v157, v86, 2, s88
	v_lshlrev_b32_e32 v162, 7, v83
	v_lshlrev_b32_e32 v163, 7, v85
	v_lshlrev_b32_e32 v164, 7, v86
	v_add_u32_e32 v165, v90, v16
	v_add_u32_e32 v166, v90, v84
	v_add_u32_e32 v167, v95, v92
	s_mov_b32 s77, 0
	v_mov_b32_e32 v83, v82
	v_mov_b32_e32 v84, v82
	v_mov_b32_e32 v85, v82
	v_mov_b32_e32 v86, v82
	v_mov_b32_e32 v87, v82
	v_mov_b32_e32 v88, v82
	v_mov_b32_e32 v89, v82
	v_mov_b32_e32 v90, v82
	v_mov_b32_e32 v91, v82
	v_mov_b32_e32 v92, v82
	v_mov_b32_e32 v93, v82
	v_mov_b32_e32 v94, v82
	v_mov_b32_e32 v95, v82
	v_mov_b32_e32 v96, v82
	v_mov_b32_e32 v97, v82
	s_barrier
	v_cndmask_b32_e64 v155, 0, v228, s[8:9]
	v_cndmask_b32_e64 v156, 0, v228, s[8:9]
	v_cndmask_b32_e64 v157, 0, v228, s[8:9]
	v_cndmask_b32_e64 v158, 0, v228, s[8:9]
	v_cndmask_b32_e64 v159, 0, v228, s[8:9]
	v_cndmask_b32_e64 v160, 0, v228, s[8:9]
	v_cndmask_b32_e64 v161, 0, v228, s[8:9]
	v_cndmask_b32_e64 v177, 0, v228, s[8:9]
	v_add_u32_e32 v155, v155, v122
	v_add_u32_e32 v156, v156, v123
	v_add_u32_e32 v157, v157, v124
	v_add_u32_e32 v158, v158, v125
	v_add_u32_e32 v159, v159, v126
	v_add_u32_e32 v160, v160, v127
	v_add_u32_e32 v161, v161, v128
	v_add_u32_e32 v177, v177, v129
	v_subrev_u32_e32 v111, s98, v108
	v_lshrrev_b32_e32 v112, 6, v119
	v_lshl_add_u32 v111, v112, 12, v111
	s_branch .LBB0_806

.LBB0_806:
	s_cmpk_lt_u32 s77, 0x206
	s_cselect_b64 s[58:59], -1, 0
	s_cmpk_gt_u32 s77, 0x205
	s_cselect_b64 s[64:65], -1, 0
	s_and_b64 vcc, exec, s[64:65]
	s_cbranch_vccnz .LBB0_810
	s_cmp_lt_u32 s77, 6
	s_cselect_b32 s44, 2, -6
	s_cselect_b32 s45, 7, 0x1ff
	s_cselect_b32 s74, 0x4000, 0
	s_add_i32 s75, s44, s77
	s_sub_i32 s44, s45, s44
	s_add_i32 s78, s52, s44
	s_and_b64 s[44:45], s[4:5], exec
	s_cselect_b32 s44, s75, s78
	s_lshl_b32 s44, s44, 5
	s_add_i32 s74, s44, s74
	s_lshl_b32 s75, s74, 12
	s_add_u32 s44, s98, s75
	s_addc_u32 s45, s99, 0
	global_load_dwordx4 v[0:3], v111, s[44:45]
	s_add_u32 s44, s44, 0x4000
	s_addc_u32 s45, s45, 0
	global_load_dwordx4 v[4:7], v111, s[44:45]
	s_add_u32 s44, s44, 0x4000
	s_addc_u32 s45, s45, 0
	global_load_dwordx4 v[8:11], v111, s[44:45]
	s_add_u32 s44, s44, 0x4000
	s_addc_u32 s45, s45, 0
	global_load_dwordx4 v[12:15], v111, s[44:45]
	s_add_u32 s44, s44, 0x4000
	s_addc_u32 s45, s45, 0
	global_load_dwordx4 v[22:25], v111, s[44:45]
	s_add_u32 s44, s44, 0x4000
	s_addc_u32 s45, s45, 0
	global_load_dwordx4 v[30:33], v111, s[44:45]
	s_add_u32 s44, s44, 0x4000
	s_addc_u32 s45, s45, 0
	global_load_dwordx4 v[38:41], v111, s[44:45]
	s_add_u32 s44, s44, 0x4000
	s_addc_u32 s45, s45, 0
	global_load_dwordx4 v[42:45], v111, s[44:45]
	s_and_saveexec_b64 s[44:45], s[10:11]
	s_cbranch_execz .LBB0_809
	v_add_u32_e32 v18, s74, v110
	v_ashrrev_i32_e32 v19, 31, v18
	v_lshl_add_u64 v[34:35], v[18:19], 4, s[48:49]
	v_lshlrev_b64 v[18:19], 11, v[18:19]
	v_lshl_add_u64 v[18:19], s[62:63], 0, v[18:19]
	global_load_dwordx4 v[18:21], v[18:19], off
	s_nop 0
	global_load_dwordx4 v[34:37], v[34:35], off

.LBB0_847:
	s_or_b64 exec, exec, s[74:75]
	s_waitcnt vmcnt(8)
	ds_write_b128 v155, v[46:49]
	s_waitcnt vmcnt(7)
	ds_write_b128 v156, v[50:53]
	s_waitcnt vmcnt(6)
	ds_write_b128 v157, v[54:57]
	s_waitcnt vmcnt(5)
	ds_write_b128 v158, v[58:61]
	s_waitcnt vmcnt(4)
	ds_write_b128 v159, v[66:69]
	s_waitcnt vmcnt(3)
	ds_write_b128 v160, v[70:73]
	s_waitcnt vmcnt(2)
	ds_write_b128 v161, v[74:77]
	s_waitcnt vmcnt(1)
	ds_write_b128 v177, v[78:81]
	v_cvt_pk_bf16_f32 v196, v94, v95
	v_cvt_pk_bf16_f32 v197, v96, v97
	ds_write_b64 v179, v[196:197] offset:55552
	v_cvt_pk_bf16_f32 v198, v90, v91
	v_cvt_pk_bf16_f32 v199, v92, v93
	ds_write_b64 v179, v[198:199] offset:55584
	v_cvt_pk_bf16_f32 v200, v86, v87
	v_cvt_pk_bf16_f32 v201, v88, v89
	ds_write_b64 v179, v[200:201] offset:55616
	v_cvt_pk_bf16_f32 v202, v82, v83
	v_cvt_pk_bf16_f32 v203, v84, v85
	ds_write_b64 v179, v[202:203] offset:55648
	s_waitcnt lgkmcnt(0)
	s_andn2_b64 vcc, exec, s[58:59]
	s_barrier
	s_cbranch_vccnz .LBB0_851
	s_cmp_lt_u32 s77, 6
	s_cselect_b32 s58, 2, -6
	s_cselect_b32 s59, 7, 0x1ff
	s_cselect_b32 s74, 0x4000, 0
	s_add_i32 s75, s58, s77
	s_sub_i32 s58, s59, s58
	s_add_i32 s58, s52, s58
	s_add_i32 s75, s75, 1
	s_add_i32 s79, s58, -1
	s_and_b64 s[58:59], s[4:5], exec
	s_cselect_b32 s58, s75, s79
	s_lshl_b32 s58, s58, 5
	s_add_i32 s74, s58, s74
	s_lshl_b32 s75, s74, 12
	s_add_u32 s58, s98, s75
	s_addc_u32 s59, s99, 0
	global_load_dwordx4 v[46:49], v111, s[58:59]
	s_add_u32 s58, s58, 0x4000
	s_addc_u32 s59, s59, 0
	global_load_dwordx4 v[50:53], v111, s[58:59]
	s_add_u32 s58, s58, 0x4000
	s_addc_u32 s59, s59, 0
	global_load_dwordx4 v[54:57], v111, s[58:59]
	s_add_u32 s58, s58, 0x4000
	s_addc_u32 s59, s59, 0
	global_load_dwordx4 v[58:61], v111, s[58:59]
	s_add_u32 s58, s58, 0x4000
	s_addc_u32 s59, s59, 0
	global_load_dwordx4 v[66:69], v111, s[58:59]
	s_add_u32 s58, s58, 0x4000
	s_addc_u32 s59, s59, 0
	global_load_dwordx4 v[70:73], v111, s[58:59]
	s_add_u32 s58, s58, 0x4000
	s_addc_u32 s59, s59, 0
	global_load_dwordx4 v[74:77], v111, s[58:59]
	s_add_u32 s58, s58, 0x4000
	s_addc_u32 s59, s59, 0
	global_load_dwordx4 v[78:81], v111, s[58:59]
	s_and_saveexec_b64 s[58:59], s[10:11]
	s_cbranch_execz .LBB0_850
	v_add_u32_e32 v26, s74, v110
	v_ashrrev_i32_e32 v27, 31, v26
	v_lshl_add_u64 v[28:29], v[26:27], 4, s[48:49]
	v_lshlrev_b64 v[26:27], 11, v[26:27]
	v_lshl_add_u64 v[26:27], s[62:63], 0, v[26:27]
	global_load_dwordx4 v[62:65], v[26:27], off
	s_nop 0
	global_load_dwordx4 v[26:29], v[28:29], off
